# sample-state streaming loops request the eight state rows of a pass together (was one 16 B load in flight per thread); FFN-down sample-row split-K loop keeps four K-steps of loads in flight
# speedup vs baseline: 1.0701x; 1.0127x over previous
; template <bool RET>
; __device__ __forceinline__ void recur_sample_item(ParamsK p, int l, int item, LAS unsigned char* lds) {
;     ...
; #pragma unroll 8
;     for (int k = kr; k < 128; k += KR) {
;         const f32x4 s = __builtin_nontemporal_load((const f32x4*)(s0 + (size_t)k * DV + vq * 4));
;         const f32x4 nw = s * ds[k] + v4 * ks[k];
;         __builtin_nontemporal_store(nw, (f32x4*)(sn + (size_t)k * DV + vq * 4));
;         o4 += nw * qs[k];
;     }
.LBB0_675:
	v_lshl_add_u64 v[132:133], v[50:51], 0, v[18:19]
	global_load_dwordx4 v[100:103], v[132:133], off nt
	v_lshl_add_u64 v[132:133], v[46:47], 0, v[18:19]
	global_load_dwordx4 v[104:107], v[132:133], off nt
	v_lshl_add_u64 v[132:133], v[42:43], 0, v[18:19]
	global_load_dwordx4 v[108:111], v[132:133], off nt
	v_lshl_add_u64 v[132:133], v[38:39], 0, v[18:19]
	global_load_dwordx4 v[112:115], v[132:133], off nt
	v_lshl_add_u64 v[132:133], v[34:35], 0, v[18:19]
	global_load_dwordx4 v[116:119], v[132:133], off nt
	v_lshl_add_u64 v[132:133], v[30:31], 0, v[18:19]
	global_load_dwordx4 v[120:123], v[132:133], off nt
	v_lshl_add_u64 v[132:133], v[26:27], 0, v[18:19]
	global_load_dwordx4 v[124:127], v[132:133], off nt
	v_lshl_add_u64 v[132:133], v[22:23], 0, v[18:19]
	global_load_dwordx4 v[128:131], v[132:133], off nt
	v_add_u32_e32 v53, 0x400, v11
	ds_read2_b32 v[60:61], v11 offset0:128 offset1:144
	ds_read2_b32 v[58:59], v53 offset1:16
	v_add_u32_e32 v0, 0x80, v0
	v_add_u32_e32 v13, 0x200, v11
	v_cmp_lt_i32_e32 vcc, -1, v0
	s_waitcnt lgkmcnt(1)
	v_pk_mul_f32 v[62:63], v[60:61], v[16:17] op_sel_hi:[0,1]
	v_pk_mul_f32 v[64:65], v[60:61], v[14:15] op_sel_hi:[0,1]
	v_lshl_add_u64 v[50:51], v[50:51], 0, s[86:87]
	s_or_b64 s[18:19], vcc, s[18:19]
	s_waitcnt vmcnt(7) lgkmcnt(0)
	v_pk_fma_f32 v[54:55], v[100:101], v[58:59], v[64:65] op_sel_hi:[1,0,1]
	v_pk_fma_f32 v[56:57], v[102:103], v[58:59], v[62:63] op_sel_hi:[1,0,1]
	v_lshl_add_u64 v[62:63], v[48:49], 0, v[18:19]
	global_store_dwordx4 v[62:63], v[54:57], off nt
	ds_read2_b32 v[62:63], v11 offset1:16
	v_mov_b32_e32 v58, v61
	v_pk_mul_f32 v[60:61], v[58:59], v[16:17] op_sel_hi:[0,1]
	v_pk_mul_f32 v[64:65], v[58:59], v[14:15] op_sel_hi:[0,1]
	v_mov_b32_e32 v58, v59
	s_waitcnt lgkmcnt(0)
	v_pk_fma_f32 v[54:55], v[54:55], v[62:63], v[2:3] op_sel_hi:[1,0,1]
	v_pk_fma_f32 v[56:57], v[56:57], v[62:63], v[4:5] op_sel_hi:[1,0,1]
	v_lshl_add_u64 v[46:47], v[46:47], 0, s[86:87]
	v_lshl_add_u64 v[48:49], v[48:49], 0, s[86:87]
	s_waitcnt vmcnt(7)
	v_pk_fma_f32 v[2:3], v[104:105], v[58:59], v[64:65] op_sel_hi:[1,0,1]
	v_pk_fma_f32 v[4:5], v[106:107], v[58:59], v[60:61] op_sel_hi:[1,0,1]
	v_lshl_add_u64 v[58:59], v[44:45], 0, v[18:19]
	global_store_dwordx4 v[58:59], v[2:5], off nt
	v_mov_b32_e32 v58, v63
	v_pk_fma_f32 v[54:55], v[2:3], v[58:59], v[54:55] op_sel_hi:[1,0,1]
	v_pk_fma_f32 v[56:57], v[4:5], v[58:59], v[56:57] op_sel_hi:[1,0,1]
	ds_read2_b32 v[58:59], v53 offset0:32 offset1:48
	ds_read2_b32 v[60:61], v11 offset0:160 offset1:176
	v_lshl_add_u64 v[42:43], v[42:43], 0, s[86:87]
	v_lshl_add_u64 v[44:45], v[44:45], 0, s[86:87]
	s_waitcnt lgkmcnt(0)
	v_pk_mul_f32 v[62:63], v[60:61], v[16:17] op_sel_hi:[0,1]
	v_pk_mul_f32 v[64:65], v[60:61], v[14:15] op_sel_hi:[0,1]
	s_waitcnt vmcnt(7)
	v_pk_fma_f32 v[2:3], v[108:109], v[58:59], v[64:65] op_sel_hi:[1,0,1]
	v_pk_fma_f32 v[4:5], v[110:111], v[58:59], v[62:63] op_sel_hi:[1,0,1]
	v_lshl_add_u64 v[62:63], v[40:41], 0, v[18:19]
	global_store_dwordx4 v[62:63], v[2:5], off nt
	ds_read2_b32 v[62:63], v11 offset0:32 offset1:48
	v_mov_b32_e32 v58, v61
	v_pk_mul_f32 v[60:61], v[58:59], v[16:17] op_sel_hi:[0,1]
	v_pk_mul_f32 v[64:65], v[58:59], v[14:15] op_sel_hi:[0,1]
	v_mov_b32_e32 v58, v59
	s_waitcnt lgkmcnt(0)
	v_pk_fma_f32 v[54:55], v[2:3], v[62:63], v[54:55] op_sel_hi:[1,0,1]
	v_pk_fma_f32 v[56:57], v[4:5], v[62:63], v[56:57] op_sel_hi:[1,0,1]
	v_lshl_add_u64 v[38:39], v[38:39], 0, s[86:87]
	v_lshl_add_u64 v[40:41], v[40:41], 0, s[86:87]
	s_waitcnt vmcnt(7)
	v_pk_fma_f32 v[2:3], v[112:113], v[58:59], v[64:65] op_sel_hi:[1,0,1]
	v_pk_fma_f32 v[4:5], v[114:115], v[58:59], v[60:61] op_sel_hi:[1,0,1]
	v_lshl_add_u64 v[58:59], v[36:37], 0, v[18:19]
	global_store_dwordx4 v[58:59], v[2:5], off nt
	v_mov_b32_e32 v58, v63
	v_pk_fma_f32 v[54:55], v[2:3], v[58:59], v[54:55] op_sel_hi:[1,0,1]
	v_pk_fma_f32 v[56:57], v[4:5], v[58:59], v[56:57] op_sel_hi:[1,0,1]
	ds_read2_b32 v[58:59], v53 offset0:64 offset1:80
	ds_read2_b32 v[60:61], v11 offset0:192 offset1:208
	v_lshl_add_u64 v[34:35], v[34:35], 0, s[86:87]
	v_lshl_add_u64 v[36:37], v[36:37], 0, s[86:87]
	s_waitcnt lgkmcnt(0)
	v_pk_mul_f32 v[62:63], v[60:61], v[16:17] op_sel_hi:[0,1]
	v_pk_mul_f32 v[64:65], v[60:61], v[14:15] op_sel_hi:[0,1]
	s_waitcnt vmcnt(7)
	v_pk_fma_f32 v[4:5], v[118:119], v[58:59], v[62:63] op_sel_hi:[1,0,1]
	v_pk_fma_f32 v[2:3], v[116:117], v[58:59], v[64:65] op_sel_hi:[1,0,1]
	v_lshl_add_u64 v[62:63], v[32:33], 0, v[18:19]
	global_store_dwordx4 v[62:63], v[2:5], off nt
	ds_read2_b32 v[62:63], v11 offset0:64 offset1:80
	v_mov_b32_e32 v58, v61
	v_pk_mul_f32 v[60:61], v[58:59], v[16:17] op_sel_hi:[0,1]
	v_pk_mul_f32 v[64:65], v[58:59], v[14:15] op_sel_hi:[0,1]
	v_mov_b32_e32 v58, v59
	s_waitcnt lgkmcnt(0)
	v_pk_fma_f32 v[54:55], v[2:3], v[62:63], v[54:55] op_sel_hi:[1,0,1]
	v_pk_fma_f32 v[56:57], v[4:5], v[62:63], v[56:57] op_sel_hi:[1,0,1]
	v_lshl_add_u64 v[30:31], v[30:31], 0, s[86:87]
	v_lshl_add_u64 v[32:33], v[32:33], 0, s[86:87]
	s_waitcnt vmcnt(7)
	v_pk_fma_f32 v[4:5], v[122:123], v[58:59], v[60:61] op_sel_hi:[1,0,1]
	v_pk_fma_f32 v[2:3], v[120:121], v[58:59], v[64:65] op_sel_hi:[1,0,1]
	v_lshl_add_u64 v[58:59], v[28:29], 0, v[18:19]
	global_store_dwordx4 v[58:59], v[2:5], off nt
	v_mov_b32_e32 v58, v63
	v_pk_fma_f32 v[54:55], v[2:3], v[58:59], v[54:55] op_sel_hi:[1,0,1]
	v_pk_fma_f32 v[56:57], v[4:5], v[58:59], v[56:57] op_sel_hi:[1,0,1]
	ds_read2_b32 v[58:59], v53 offset0:96 offset1:112
	ds_read2_b32 v[60:61], v11 offset0:224 offset1:240
	v_lshl_add_u64 v[26:27], v[26:27], 0, s[86:87]
	v_lshl_add_u64 v[28:29], v[28:29], 0, s[86:87]
	s_waitcnt lgkmcnt(0)
	v_pk_mul_f32 v[62:63], v[60:61], v[16:17] op_sel_hi:[0,1]
	v_pk_mul_f32 v[64:65], v[60:61], v[14:15] op_sel_hi:[0,1]
	s_waitcnt vmcnt(7)
	v_pk_fma_f32 v[4:5], v[126:127], v[58:59], v[62:63] op_sel_hi:[1,0,1]
	v_pk_fma_f32 v[2:3], v[124:125], v[58:59], v[64:65] op_sel_hi:[1,0,1]
	v_lshl_add_u64 v[62:63], v[24:25], 0, v[18:19]
	global_store_dwordx4 v[62:63], v[2:5], off nt
	ds_read2_b32 v[62:63], v11 offset0:96 offset1:112
	v_mov_b32_e32 v58, v61
	v_pk_mul_f32 v[60:61], v[58:59], v[16:17] op_sel_hi:[0,1]
	v_pk_mul_f32 v[64:65], v[58:59], v[14:15] op_sel_hi:[0,1]
	v_mov_b32_e32 v58, v59
	s_waitcnt lgkmcnt(0)
	v_pk_fma_f32 v[54:55], v[2:3], v[62:63], v[54:55] op_sel_hi:[1,0,1]
	v_pk_fma_f32 v[56:57], v[4:5], v[62:63], v[56:57] op_sel_hi:[1,0,1]
	v_lshl_add_u64 v[22:23], v[22:23], 0, s[86:87]
	v_lshl_add_u64 v[24:25], v[24:25], 0, s[86:87]
	v_mov_b32_e32 v11, v13
	s_waitcnt vmcnt(7)
	v_pk_fma_f32 v[4:5], v[130:131], v[58:59], v[60:61] op_sel_hi:[1,0,1]
	v_pk_fma_f32 v[2:3], v[128:129], v[58:59], v[64:65] op_sel_hi:[1,0,1]
	v_lshl_add_u64 v[58:59], v[20:21], 0, v[18:19]
	global_store_dwordx4 v[58:59], v[2:5], off nt
	v_mov_b32_e32 v58, v63
	v_lshl_add_u64 v[20:21], v[20:21], 0, s[86:87]
	v_pk_fma_f32 v[4:5], v[4:5], v[58:59], v[56:57] op_sel_hi:[1,0,1]
	v_pk_fma_f32 v[2:3], v[2:3], v[58:59], v[54:55] op_sel_hi:[1,0,1]
	s_andn2_b64 exec, exec, s[18:19]
	s_cbranch_execnz .LBB0_675
	s_or_b64 exec, exec, s[18:19]

; template <bool RET>
; __device__ __forceinline__ void recur_sample_item(ParamsK p, int l, int item, LAS unsigned char* lds) {
;     ...
; #pragma unroll 8
;     for (int k = kr; k < 128; k += KR) {
;         const f32x4 s = __builtin_nontemporal_load((const f32x4*)(s0 + (size_t)k * DV + vq * 4));
;         const f32x4 nw = s * ds[k] + v4 * ks[k];
;         __builtin_nontemporal_store(nw, (f32x4*)(sn + (size_t)k * DV + vq * 4));
;         o4 += nw * qs[k];
;     }
.LBB0_691:
	v_lshl_add_u64 v[132:133], v[48:49], 0, v[16:17]
	global_load_dwordx4 v[100:103], v[132:133], off nt
	v_lshl_add_u64 v[132:133], v[44:45], 0, v[16:17]
	global_load_dwordx4 v[104:107], v[132:133], off nt
	v_lshl_add_u64 v[132:133], v[40:41], 0, v[16:17]
	global_load_dwordx4 v[108:111], v[132:133], off nt
	v_lshl_add_u64 v[132:133], v[36:37], 0, v[16:17]
	global_load_dwordx4 v[112:115], v[132:133], off nt
	v_lshl_add_u64 v[132:133], v[32:33], 0, v[16:17]
	global_load_dwordx4 v[116:119], v[132:133], off nt
	v_lshl_add_u64 v[132:133], v[28:29], 0, v[16:17]
	global_load_dwordx4 v[120:123], v[132:133], off nt
	v_lshl_add_u64 v[132:133], v[24:25], 0, v[16:17]
	global_load_dwordx4 v[124:127], v[132:133], off nt
	v_lshl_add_u64 v[132:133], v[20:21], 0, v[16:17]
	global_load_dwordx4 v[128:131], v[132:133], off nt
	v_add_u32_e32 v11, 0x400, v0
	ds_read2_b32 v[56:57], v11 offset1:8
	ds_read2_b32 v[58:59], v0 offset0:128 offset1:136
	v_add_u32_e32 v9, 64, v9
	v_cmp_lt_i32_e32 vcc, 63, v9
	v_lshl_add_u64 v[48:49], v[48:49], 0, s[86:87]
	s_or_b64 s[20:21], vcc, s[20:21]
	s_waitcnt lgkmcnt(0)
	v_pk_mul_f32 v[60:61], v[58:59], v[14:15] op_sel_hi:[0,1]
	v_pk_mul_f32 v[62:63], v[58:59], v[12:13] op_sel_hi:[0,1]
	s_waitcnt vmcnt(7)
	v_pk_fma_f32 v[52:53], v[100:101], v[56:57], v[62:63] op_sel_hi:[1,0,1]
	v_pk_fma_f32 v[54:55], v[102:103], v[56:57], v[60:61] op_sel_hi:[1,0,1]
	v_lshl_add_u64 v[60:61], v[46:47], 0, v[16:17]
	global_store_dwordx4 v[60:61], v[52:55], off nt
	ds_read2_b32 v[60:61], v0 offset1:8
	v_mov_b32_e32 v56, v59
	v_pk_mul_f32 v[58:59], v[56:57], v[14:15] op_sel_hi:[0,1]
	v_pk_mul_f32 v[62:63], v[56:57], v[12:13] op_sel_hi:[0,1]
	v_mov_b32_e32 v56, v57
	s_waitcnt lgkmcnt(0)
	v_pk_fma_f32 v[52:53], v[52:53], v[60:61], v[2:3] op_sel_hi:[1,0,1]
	v_pk_fma_f32 v[54:55], v[54:55], v[60:61], v[4:5] op_sel_hi:[1,0,1]
	v_lshl_add_u64 v[44:45], v[44:45], 0, s[86:87]
	v_lshl_add_u64 v[46:47], v[46:47], 0, s[86:87]
	s_waitcnt vmcnt(7)
	v_pk_fma_f32 v[2:3], v[104:105], v[56:57], v[62:63] op_sel_hi:[1,0,1]
	v_pk_fma_f32 v[4:5], v[106:107], v[56:57], v[58:59] op_sel_hi:[1,0,1]
	v_lshl_add_u64 v[56:57], v[42:43], 0, v[16:17]
	global_store_dwordx4 v[56:57], v[2:5], off nt
	v_mov_b32_e32 v56, v61
	v_pk_fma_f32 v[52:53], v[2:3], v[56:57], v[52:53] op_sel_hi:[1,0,1]
	v_pk_fma_f32 v[54:55], v[4:5], v[56:57], v[54:55] op_sel_hi:[1,0,1]
	ds_read2_b32 v[56:57], v11 offset0:16 offset1:24
	ds_read2_b32 v[58:59], v0 offset0:144 offset1:152
	v_lshl_add_u64 v[40:41], v[40:41], 0, s[86:87]
	v_lshl_add_u64 v[42:43], v[42:43], 0, s[86:87]
	s_waitcnt lgkmcnt(0)
	v_pk_mul_f32 v[60:61], v[58:59], v[14:15] op_sel_hi:[0,1]
	v_pk_mul_f32 v[62:63], v[58:59], v[12:13] op_sel_hi:[0,1]
	s_waitcnt vmcnt(7)
	v_pk_fma_f32 v[2:3], v[108:109], v[56:57], v[62:63] op_sel_hi:[1,0,1]
	v_pk_fma_f32 v[4:5], v[110:111], v[56:57], v[60:61] op_sel_hi:[1,0,1]
	v_lshl_add_u64 v[60:61], v[38:39], 0, v[16:17]
	global_store_dwordx4 v[60:61], v[2:5], off nt
	ds_read2_b32 v[60:61], v0 offset0:16 offset1:24
	v_mov_b32_e32 v56, v59
	v_pk_mul_f32 v[58:59], v[56:57], v[14:15] op_sel_hi:[0,1]
	v_pk_mul_f32 v[62:63], v[56:57], v[12:13] op_sel_hi:[0,1]
	v_mov_b32_e32 v56, v57
	s_waitcnt lgkmcnt(0)
	v_pk_fma_f32 v[52:53], v[2:3], v[60:61], v[52:53] op_sel_hi:[1,0,1]
	v_pk_fma_f32 v[54:55], v[4:5], v[60:61], v[54:55] op_sel_hi:[1,0,1]
	v_lshl_add_u64 v[36:37], v[36:37], 0, s[86:87]
	v_lshl_add_u64 v[38:39], v[38:39], 0, s[86:87]
	s_waitcnt vmcnt(7)
	v_pk_fma_f32 v[2:3], v[112:113], v[56:57], v[62:63] op_sel_hi:[1,0,1]
	v_pk_fma_f32 v[4:5], v[114:115], v[56:57], v[58:59] op_sel_hi:[1,0,1]
	v_lshl_add_u64 v[56:57], v[34:35], 0, v[16:17]
	global_store_dwordx4 v[56:57], v[2:5], off nt
	v_mov_b32_e32 v56, v61
	v_pk_fma_f32 v[52:53], v[2:3], v[56:57], v[52:53] op_sel_hi:[1,0,1]
	v_pk_fma_f32 v[54:55], v[4:5], v[56:57], v[54:55] op_sel_hi:[1,0,1]
	ds_read2_b32 v[56:57], v11 offset0:32 offset1:40
	ds_read2_b32 v[58:59], v0 offset0:160 offset1:168
	v_lshl_add_u64 v[32:33], v[32:33], 0, s[86:87]
	v_lshl_add_u64 v[34:35], v[34:35], 0, s[86:87]
	s_waitcnt lgkmcnt(0)
	v_pk_mul_f32 v[60:61], v[58:59], v[14:15] op_sel_hi:[0,1]
	v_pk_mul_f32 v[62:63], v[58:59], v[12:13] op_sel_hi:[0,1]
	s_waitcnt vmcnt(7)
	v_pk_fma_f32 v[4:5], v[118:119], v[56:57], v[60:61] op_sel_hi:[1,0,1]
	v_pk_fma_f32 v[2:3], v[116:117], v[56:57], v[62:63] op_sel_hi:[1,0,1]
	v_lshl_add_u64 v[60:61], v[30:31], 0, v[16:17]
	global_store_dwordx4 v[60:61], v[2:5], off nt
	ds_read2_b32 v[60:61], v0 offset0:32 offset1:40
	v_mov_b32_e32 v56, v59
	v_pk_mul_f32 v[58:59], v[56:57], v[14:15] op_sel_hi:[0,1]
	v_pk_mul_f32 v[62:63], v[56:57], v[12:13] op_sel_hi:[0,1]
	v_mov_b32_e32 v56, v57
	s_waitcnt lgkmcnt(0)
	v_pk_fma_f32 v[52:53], v[2:3], v[60:61], v[52:53] op_sel_hi:[1,0,1]
	v_pk_fma_f32 v[54:55], v[4:5], v[60:61], v[54:55] op_sel_hi:[1,0,1]
	v_lshl_add_u64 v[28:29], v[28:29], 0, s[86:87]
	v_lshl_add_u64 v[30:31], v[30:31], 0, s[86:87]
	s_waitcnt vmcnt(7)
	v_pk_fma_f32 v[4:5], v[122:123], v[56:57], v[58:59] op_sel_hi:[1,0,1]
	v_pk_fma_f32 v[2:3], v[120:121], v[56:57], v[62:63] op_sel_hi:[1,0,1]
	v_lshl_add_u64 v[56:57], v[26:27], 0, v[16:17]
	global_store_dwordx4 v[56:57], v[2:5], off nt
	v_mov_b32_e32 v56, v61
	v_pk_fma_f32 v[52:53], v[2:3], v[56:57], v[52:53] op_sel_hi:[1,0,1]
	v_pk_fma_f32 v[54:55], v[4:5], v[56:57], v[54:55] op_sel_hi:[1,0,1]
	ds_read2_b32 v[56:57], v11 offset0:48 offset1:56
	ds_read2_b32 v[58:59], v0 offset0:176 offset1:184
	v_lshl_add_u64 v[24:25], v[24:25], 0, s[86:87]
	v_lshl_add_u64 v[26:27], v[26:27], 0, s[86:87]
	s_waitcnt lgkmcnt(0)
	v_pk_mul_f32 v[60:61], v[58:59], v[14:15] op_sel_hi:[0,1]
	v_pk_mul_f32 v[62:63], v[58:59], v[12:13] op_sel_hi:[0,1]
	s_waitcnt vmcnt(7)
	v_pk_fma_f32 v[4:5], v[126:127], v[56:57], v[60:61] op_sel_hi:[1,0,1]
	v_pk_fma_f32 v[2:3], v[124:125], v[56:57], v[62:63] op_sel_hi:[1,0,1]
	v_lshl_add_u64 v[60:61], v[22:23], 0, v[16:17]
	global_store_dwordx4 v[60:61], v[2:5], off nt
	ds_read2_b32 v[60:61], v0 offset0:48 offset1:56
	v_mov_b32_e32 v56, v59
	v_pk_mul_f32 v[58:59], v[56:57], v[14:15] op_sel_hi:[0,1]
	v_pk_mul_f32 v[62:63], v[56:57], v[12:13] op_sel_hi:[0,1]
	v_mov_b32_e32 v56, v57
	s_waitcnt lgkmcnt(0)
	v_pk_fma_f32 v[52:53], v[2:3], v[60:61], v[52:53] op_sel_hi:[1,0,1]
	v_pk_fma_f32 v[54:55], v[4:5], v[60:61], v[54:55] op_sel_hi:[1,0,1]
	v_add_u32_e32 v0, 0x100, v0
	v_lshl_add_u64 v[20:21], v[20:21], 0, s[86:87]
	v_lshl_add_u64 v[22:23], v[22:23], 0, s[86:87]
	s_waitcnt vmcnt(7)
	v_pk_fma_f32 v[4:5], v[130:131], v[56:57], v[58:59] op_sel_hi:[1,0,1]
	v_pk_fma_f32 v[2:3], v[128:129], v[56:57], v[62:63] op_sel_hi:[1,0,1]
	v_lshl_add_u64 v[56:57], v[18:19], 0, v[16:17]
	global_store_dwordx4 v[56:57], v[2:5], off nt
	v_mov_b32_e32 v56, v61
	v_lshl_add_u64 v[18:19], v[18:19], 0, s[86:87]
	v_pk_fma_f32 v[4:5], v[4:5], v[56:57], v[54:55] op_sel_hi:[1,0,1]
	v_pk_fma_f32 v[2:3], v[2:3], v[56:57], v[52:53] op_sel_hi:[1,0,1]
	s_andn2_b64 exec, exec, s[20:21]
	s_cbranch_execnz .LBB0_691
	s_or_b64 exec, exec, s[20:21]

; __device__ __forceinline__ void skinny_resid(const bf16_t* A, int lda, const bf16_t* Wt, int ldb, int K, const XSrc res, float* out, LAS unsigned char* lds) {
;     ...
;         const int ksper = K / 256, k0 = w * ksper * 32;
;         f32x4 acc[4];
; #pragma unroll
;         for (int mt = 0; mt < 4; ++mt) acc[mt] = (f32x4){0.f, 0.f, 0.f, 0.f};
; #pragma unroll 4
;         for (int ks = 0; ks < ksper; ++ks) {
;             const int k = k0 + ks * 32;
;             const bf16x8 b = *(const bf16x8*)(bp + k);
;             bf16x8 a[4];
; #pragma unroll
;             for (int mt = 0; mt < 4; ++mt) a[mt] = *(const bf16x8*)(ap + (size_t)mt * 16 * lda + k);
; #pragma unroll
;             for (int mt = 0; mt < 4; ++mt) acc[mt] = __builtin_amdgcn_mfma_f32_16x16x32_bf16(a[mt], b, acc[mt], 0, 0, 0);
;         }
.LBB0_1684:
	s_and_b32 s8, s6, 64
	s_bitset1_b32 s8, 13
	v_or_b32_e32 v0, s8, v74
	v_mul_u32_u24_e32 v0, 0x1600, v0
	v_lshlrev_b32_e32 v0, 1, v0
	v_lshl_add_u64 v[22:23], v[26:27], 0, v[0:1]
	v_lshl_add_u64 v[20:21], v[28:29], 1, v[22:23]
	v_add_co_u32_e32 v24, vcc, s88, v20
	s_and_b32 s7, s5, -16
	s_nop 0
	v_addc_co_u32_e32 v25, vcc, 0, v21, vcc
	v_add_co_u32_e32 v72, vcc, s89, v20
	v_or_b32_e32 v2, s7, v74
	s_nop 0
	v_addc_co_u32_e32 v73, vcc, 0, v21, vcc
	v_add_co_u32_e32 v98, vcc, s57, v20
	v_mad_i64_i32 v[18:19], s[12:13], v2, s60, v[70:71]
	s_nop 0
	v_addc_co_u32_e32 v99, vcc, 0, v21, vcc
	global_load_dwordx4 v[102:105], v[18:19], off
	global_load_dwordx4 v[106:109], v[20:21], off
	global_load_dwordx4 v[110:113], v[24:25], off
	global_load_dwordx4 v[114:117], v[72:73], off
	global_load_dwordx4 v[118:121], v[98:99], off
	global_load_dwordx4 v[156:159], v[18:19], off offset:64
	global_load_dwordx4 v[160:163], v[20:21], off offset:64
	global_load_dwordx4 v[164:167], v[24:25], off offset:64
	global_load_dwordx4 v[168:171], v[72:73], off offset:64
	global_load_dwordx4 v[172:175], v[98:99], off offset:64
	global_load_dwordx4 v[194:197], v[18:19], off offset:128
	global_load_dwordx4 v[198:201], v[20:21], off offset:128
	global_load_dwordx4 v[202:205], v[24:25], off offset:128
	global_load_dwordx4 v[206:209], v[72:73], off offset:128
	global_load_dwordx4 v[210:213], v[98:99], off offset:128
	global_load_dwordx4 v[214:217], v[18:19], off offset:192
	global_load_dwordx4 v[218:221], v[20:21], off offset:192
	global_load_dwordx4 v[222:225], v[24:25], off offset:192
	global_load_dwordx4 v[226:229], v[72:73], off offset:192
	global_load_dwordx4 v[230:233], v[98:99], off offset:192
	v_or_b32_e32 v0, s8, v76
	s_add_i32 s4, s4, s74
	s_add_i32 s5, s5, s97
	s_add_i32 s6, s6, s55
	s_cmpk_lt_i32 s4, 0x100
	s_waitcnt vmcnt(15)
	v_mfma_f32_16x16x32_bf16 v[2:5], v[106:109], v[102:105], 0
	v_mfma_f32_16x16x32_bf16 v[6:9], v[110:113], v[102:105], 0
	v_mfma_f32_16x16x32_bf16 v[10:13], v[114:117], v[102:105], 0
	v_mfma_f32_16x16x32_bf16 v[14:17], v[118:121], v[102:105], 0
	global_load_dwordx4 v[102:105], v[18:19], off offset:256
	global_load_dwordx4 v[106:109], v[20:21], off offset:256
	global_load_dwordx4 v[110:113], v[24:25], off offset:256
	global_load_dwordx4 v[114:117], v[72:73], off offset:256
	global_load_dwordx4 v[118:121], v[98:99], off offset:256
	s_waitcnt vmcnt(15)
	v_mfma_f32_16x16x32_bf16 v[2:5], v[160:163], v[156:159], v[2:5]
	v_mfma_f32_16x16x32_bf16 v[6:9], v[164:167], v[156:159], v[6:9]
	v_mfma_f32_16x16x32_bf16 v[10:13], v[168:171], v[156:159], v[10:13]
	v_mfma_f32_16x16x32_bf16 v[14:17], v[172:175], v[156:159], v[14:17]
	global_load_dwordx4 v[156:159], v[18:19], off offset:320
	global_load_dwordx4 v[160:163], v[20:21], off offset:320
	global_load_dwordx4 v[164:167], v[24:25], off offset:320
	global_load_dwordx4 v[168:171], v[72:73], off offset:320
	global_load_dwordx4 v[172:175], v[98:99], off offset:320
	s_waitcnt vmcnt(15)
	v_mfma_f32_16x16x32_bf16 v[2:5], v[198:201], v[194:197], v[2:5]
	v_mfma_f32_16x16x32_bf16 v[6:9], v[202:205], v[194:197], v[6:9]
	v_mfma_f32_16x16x32_bf16 v[10:13], v[206:209], v[194:197], v[10:13]
	v_mfma_f32_16x16x32_bf16 v[14:17], v[210:213], v[194:197], v[14:17]
	global_load_dwordx4 v[194:197], v[18:19], off offset:384
	global_load_dwordx4 v[198:201], v[20:21], off offset:384
	global_load_dwordx4 v[202:205], v[24:25], off offset:384
	global_load_dwordx4 v[206:209], v[72:73], off offset:384
	global_load_dwordx4 v[210:213], v[98:99], off offset:384
	s_waitcnt vmcnt(15)
	v_mfma_f32_16x16x32_bf16 v[2:5], v[218:221], v[214:217], v[2:5]
	v_mfma_f32_16x16x32_bf16 v[6:9], v[222:225], v[214:217], v[6:9]
	v_mfma_f32_16x16x32_bf16 v[10:13], v[226:229], v[214:217], v[10:13]
	v_mfma_f32_16x16x32_bf16 v[14:17], v[230:233], v[214:217], v[14:17]
	global_load_dwordx4 v[214:217], v[18:19], off offset:448
	global_load_dwordx4 v[218:221], v[20:21], off offset:448
	global_load_dwordx4 v[222:225], v[24:25], off offset:448
	global_load_dwordx4 v[226:229], v[72:73], off offset:448
	global_load_dwordx4 v[230:233], v[98:99], off offset:448
	s_waitcnt vmcnt(15)
	v_mfma_f32_16x16x32_bf16 v[2:5], v[106:109], v[102:105], v[2:5]
	v_mfma_f32_16x16x32_bf16 v[6:9], v[110:113], v[102:105], v[6:9]
	v_mfma_f32_16x16x32_bf16 v[10:13], v[114:117], v[102:105], v[10:13]
	v_mfma_f32_16x16x32_bf16 v[14:17], v[118:121], v[102:105], v[14:17]
	global_load_dwordx4 v[102:105], v[18:19], off offset:512
	global_load_dwordx4 v[106:109], v[20:21], off offset:512
	global_load_dwordx4 v[110:113], v[24:25], off offset:512
	global_load_dwordx4 v[114:117], v[72:73], off offset:512
	global_load_dwordx4 v[118:121], v[98:99], off offset:512
	s_waitcnt vmcnt(15)
	v_mfma_f32_16x16x32_bf16 v[2:5], v[160:163], v[156:159], v[2:5]
	v_mfma_f32_16x16x32_bf16 v[6:9], v[164:167], v[156:159], v[6:9]
	v_mfma_f32_16x16x32_bf16 v[10:13], v[168:171], v[156:159], v[10:13]
	v_mfma_f32_16x16x32_bf16 v[14:17], v[172:175], v[156:159], v[14:17]
	global_load_dwordx4 v[156:159], v[18:19], off offset:576
	global_load_dwordx4 v[160:163], v[20:21], off offset:576
	global_load_dwordx4 v[164:167], v[24:25], off offset:576
	global_load_dwordx4 v[168:171], v[72:73], off offset:576
	global_load_dwordx4 v[172:175], v[98:99], off offset:576
	s_waitcnt vmcnt(15)
	v_mfma_f32_16x16x32_bf16 v[2:5], v[198:201], v[194:197], v[2:5]
	v_mfma_f32_16x16x32_bf16 v[6:9], v[202:205], v[194:197], v[6:9]
	v_mfma_f32_16x16x32_bf16 v[10:13], v[206:209], v[194:197], v[10:13]
	v_mfma_f32_16x16x32_bf16 v[14:17], v[210:213], v[194:197], v[14:17]
	global_load_dwordx4 v[194:197], v[18:19], off offset:640
	global_load_dwordx4 v[198:201], v[20:21], off offset:640
	global_load_dwordx4 v[202:205], v[24:25], off offset:640
	global_load_dwordx4 v[206:209], v[72:73], off offset:640
	global_load_dwordx4 v[210:213], v[98:99], off offset:640
	s_waitcnt vmcnt(15)
; __device__ __forceinline__ void skinny_resid(const bf16_t* A, int lda, const bf16_t* Wt, int ldb, int K, const XSrc res, float* out, LAS unsigned char* lds) {
;     ...
; #pragma unroll 4
;         for (int ks = 0; ks < ksper; ++ks) {
;             const int k = k0 + ks * 32;
;             const bf16x8 b = *(const bf16x8*)(bp + k);
;             bf16x8 a[4];
; #pragma unroll
;             for (int mt = 0; mt < 4; ++mt) a[mt] = *(const bf16x8*)(ap + (size_t)mt * 16 * lda + k);
; #pragma unroll
;             for (int mt = 0; mt < 4; ++mt) acc[mt] = __builtin_amdgcn_mfma_f32_16x16x32_bf16(a[mt], b, acc[mt], 0, 0, 0);
;         }
	v_mfma_f32_16x16x32_bf16 v[2:5], v[218:221], v[214:217], v[2:5]
	v_mfma_f32_16x16x32_bf16 v[6:9], v[222:225], v[214:217], v[6:9]
	v_mfma_f32_16x16x32_bf16 v[10:13], v[226:229], v[214:217], v[10:13]
	v_mfma_f32_16x16x32_bf16 v[14:17], v[230:233], v[214:217], v[14:17]
	global_load_dwordx4 v[214:217], v[18:19], off offset:704
	global_load_dwordx4 v[218:221], v[20:21], off offset:704
	global_load_dwordx4 v[222:225], v[24:25], off offset:704
	global_load_dwordx4 v[226:229], v[72:73], off offset:704
	global_load_dwordx4 v[230:233], v[98:99], off offset:704
	s_waitcnt vmcnt(15)
	v_mfma_f32_16x16x32_bf16 v[2:5], v[106:109], v[102:105], v[2:5]
	v_mfma_f32_16x16x32_bf16 v[6:9], v[110:113], v[102:105], v[6:9]
	v_mfma_f32_16x16x32_bf16 v[10:13], v[114:117], v[102:105], v[10:13]
	v_mfma_f32_16x16x32_bf16 v[14:17], v[118:121], v[102:105], v[14:17]
	global_load_dwordx4 v[102:105], v[18:19], off offset:768
	global_load_dwordx4 v[106:109], v[20:21], off offset:768
	global_load_dwordx4 v[110:113], v[24:25], off offset:768
	global_load_dwordx4 v[114:117], v[72:73], off offset:768
	global_load_dwordx4 v[118:121], v[98:99], off offset:768
	s_waitcnt vmcnt(15)
	v_mfma_f32_16x16x32_bf16 v[2:5], v[160:163], v[156:159], v[2:5]
	v_mfma_f32_16x16x32_bf16 v[6:9], v[164:167], v[156:159], v[6:9]
	v_mfma_f32_16x16x32_bf16 v[10:13], v[168:171], v[156:159], v[10:13]
	v_mfma_f32_16x16x32_bf16 v[14:17], v[172:175], v[156:159], v[14:17]
	global_load_dwordx4 v[156:159], v[18:19], off offset:832
	global_load_dwordx4 v[160:163], v[20:21], off offset:832
	global_load_dwordx4 v[164:167], v[24:25], off offset:832
	global_load_dwordx4 v[168:171], v[72:73], off offset:832
	global_load_dwordx4 v[172:175], v[98:99], off offset:832
	s_waitcnt vmcnt(15)
	v_mfma_f32_16x16x32_bf16 v[2:5], v[198:201], v[194:197], v[2:5]
	v_mfma_f32_16x16x32_bf16 v[6:9], v[202:205], v[194:197], v[6:9]
	v_mfma_f32_16x16x32_bf16 v[10:13], v[206:209], v[194:197], v[10:13]
	v_mfma_f32_16x16x32_bf16 v[14:17], v[210:213], v[194:197], v[14:17]
	global_load_dwordx4 v[194:197], v[18:19], off offset:896
	global_load_dwordx4 v[198:201], v[20:21], off offset:896
	global_load_dwordx4 v[202:205], v[24:25], off offset:896
	global_load_dwordx4 v[206:209], v[72:73], off offset:896
	global_load_dwordx4 v[210:213], v[98:99], off offset:896
	s_waitcnt vmcnt(15)
	v_mfma_f32_16x16x32_bf16 v[2:5], v[218:221], v[214:217], v[2:5]
	v_mfma_f32_16x16x32_bf16 v[6:9], v[222:225], v[214:217], v[6:9]
	v_mfma_f32_16x16x32_bf16 v[10:13], v[226:229], v[214:217], v[10:13]
	v_mfma_f32_16x16x32_bf16 v[14:17], v[230:233], v[214:217], v[14:17]
	global_load_dwordx4 v[214:217], v[18:19], off offset:960
	global_load_dwordx4 v[218:221], v[20:21], off offset:960
	global_load_dwordx4 v[222:225], v[24:25], off offset:960
	global_load_dwordx4 v[226:229], v[72:73], off offset:960
	global_load_dwordx4 v[230:233], v[98:99], off offset:960
	s_waitcnt vmcnt(15)
	v_mfma_f32_16x16x32_bf16 v[2:5], v[106:109], v[102:105], v[2:5]
	v_mfma_f32_16x16x32_bf16 v[6:9], v[110:113], v[102:105], v[6:9]
	v_mfma_f32_16x16x32_bf16 v[10:13], v[114:117], v[102:105], v[10:13]
	v_mfma_f32_16x16x32_bf16 v[14:17], v[118:121], v[102:105], v[14:17]
	global_load_dwordx4 v[102:105], v[18:19], off offset:1024
	global_load_dwordx4 v[106:109], v[20:21], off offset:1024
	global_load_dwordx4 v[110:113], v[24:25], off offset:1024
	global_load_dwordx4 v[114:117], v[72:73], off offset:1024
	global_load_dwordx4 v[118:121], v[98:99], off offset:1024
	s_waitcnt vmcnt(15)
	v_mfma_f32_16x16x32_bf16 v[2:5], v[160:163], v[156:159], v[2:5]
	v_mfma_f32_16x16x32_bf16 v[6:9], v[164:167], v[156:159], v[6:9]
	v_mfma_f32_16x16x32_bf16 v[10:13], v[168:171], v[156:159], v[10:13]
	v_mfma_f32_16x16x32_bf16 v[14:17], v[172:175], v[156:159], v[14:17]
	global_load_dwordx4 v[156:159], v[18:19], off offset:1088
	global_load_dwordx4 v[160:163], v[20:21], off offset:1088
	global_load_dwordx4 v[164:167], v[24:25], off offset:1088
	global_load_dwordx4 v[168:171], v[72:73], off offset:1088
	global_load_dwordx4 v[172:175], v[98:99], off offset:1088
	s_waitcnt vmcnt(15)
	v_mfma_f32_16x16x32_bf16 v[2:5], v[198:201], v[194:197], v[2:5]
	v_mfma_f32_16x16x32_bf16 v[6:9], v[202:205], v[194:197], v[6:9]
	v_mfma_f32_16x16x32_bf16 v[10:13], v[206:209], v[194:197], v[10:13]
	v_mfma_f32_16x16x32_bf16 v[14:17], v[210:213], v[194:197], v[14:17]
	global_load_dwordx4 v[194:197], v[18:19], off offset:1152
	global_load_dwordx4 v[198:201], v[20:21], off offset:1152
	global_load_dwordx4 v[202:205], v[24:25], off offset:1152
	global_load_dwordx4 v[206:209], v[72:73], off offset:1152
	global_load_dwordx4 v[210:213], v[98:99], off offset:1152
	s_waitcnt vmcnt(15)
	v_mfma_f32_16x16x32_bf16 v[2:5], v[218:221], v[214:217], v[2:5]
	v_mfma_f32_16x16x32_bf16 v[6:9], v[222:225], v[214:217], v[6:9]
	v_mfma_f32_16x16x32_bf16 v[10:13], v[226:229], v[214:217], v[10:13]
	v_mfma_f32_16x16x32_bf16 v[14:17], v[230:233], v[214:217], v[14:17]
	global_load_dwordx4 v[214:217], v[18:19], off offset:1216
	global_load_dwordx4 v[218:221], v[20:21], off offset:1216
	global_load_dwordx4 v[222:225], v[24:25], off offset:1216
	global_load_dwordx4 v[226:229], v[72:73], off offset:1216
	global_load_dwordx4 v[230:233], v[98:99], off offset:1216
	s_waitcnt vmcnt(15)
; #define LAS __attribute__((address_space(3)))
; __device__ __forceinline__ void skinny_resid(const bf16_t* A, int lda, const bf16_t* Wt, int ldb, int K, const XSrc res, float* out, LAS unsigned char* lds) {
;     ...
; #pragma unroll 4
;         for (int ks = 0; ks < ksper; ++ks) {
;             const int k = k0 + ks * 32;
;             const bf16x8 b = *(const bf16x8*)(bp + k);
;             bf16x8 a[4];
; #pragma unroll
;             for (int mt = 0; mt < 4; ++mt) a[mt] = *(const bf16x8*)(ap + (size_t)mt * 16 * lda + k);
; #pragma unroll
;             for (int mt = 0; mt < 4; ++mt) acc[mt] = __builtin_amdgcn_mfma_f32_16x16x32_bf16(a[mt], b, acc[mt], 0, 0, 0);
;         }
; #pragma unroll
;         for (int mt = 0; mt < 4; ++mt) *(LAS f32x4*)(red + w * 1024 + (mt * 64 + lane) * 4) = acc[mt];
;         __syncthreads();
; #pragma unroll
;         for (int h = 0; h < 2; ++h) {
;             const int e = tid + h * 512;
;             float sum = 0.f;
; #pragma unroll
;             for (int ww = 0; ww < 8; ++ww) sum += red[ww * 1024 + e];
;             const int mt = e >> 8, ln = (e >> 2) & 63, j = e & 3;
;             const int row = NPROMPT + rh * 64 + mt * 16 + (ln >> 4) * 4 + j, col = cg * 16 + (ln & 15);
;             out[(size_t)row * DM + col] = res.row(row)[col] + sum;
;         }
	v_mfma_f32_16x16x32_bf16 v[2:5], v[106:109], v[102:105], v[2:5]
	v_mfma_f32_16x16x32_bf16 v[6:9], v[110:113], v[102:105], v[6:9]
	v_mfma_f32_16x16x32_bf16 v[10:13], v[114:117], v[102:105], v[10:13]
	v_mfma_f32_16x16x32_bf16 v[14:17], v[118:121], v[102:105], v[14:17]
	global_load_dwordx4 v[102:105], v[18:19], off offset:1280
	global_load_dwordx4 v[106:109], v[20:21], off offset:1280
	global_load_dwordx4 v[110:113], v[24:25], off offset:1280
	global_load_dwordx4 v[114:117], v[72:73], off offset:1280
	global_load_dwordx4 v[118:121], v[98:99], off offset:1280
	s_waitcnt vmcnt(15)
	v_mfma_f32_16x16x32_bf16 v[2:5], v[160:163], v[156:159], v[2:5]
	v_mfma_f32_16x16x32_bf16 v[6:9], v[164:167], v[156:159], v[6:9]
	v_mfma_f32_16x16x32_bf16 v[10:13], v[168:171], v[156:159], v[10:13]
	v_mfma_f32_16x16x32_bf16 v[14:17], v[172:175], v[156:159], v[14:17]
	global_load_dwordx4 v[156:159], v[18:19], off offset:1344
	global_load_dwordx4 v[160:163], v[20:21], off offset:1344
	global_load_dwordx4 v[164:167], v[24:25], off offset:1344
	global_load_dwordx4 v[168:171], v[72:73], off offset:1344
	global_load_dwordx4 v[172:175], v[98:99], off offset:1344
	s_waitcnt vmcnt(15)
	v_mfma_f32_16x16x32_bf16 v[2:5], v[198:201], v[194:197], v[2:5]
	v_mfma_f32_16x16x32_bf16 v[6:9], v[202:205], v[194:197], v[6:9]
	v_mfma_f32_16x16x32_bf16 v[10:13], v[206:209], v[194:197], v[10:13]
	v_mfma_f32_16x16x32_bf16 v[14:17], v[210:213], v[194:197], v[14:17]
	s_waitcnt vmcnt(10)
	v_mfma_f32_16x16x32_bf16 v[2:5], v[218:221], v[214:217], v[2:5]
	v_mfma_f32_16x16x32_bf16 v[6:9], v[222:225], v[214:217], v[6:9]
	v_mfma_f32_16x16x32_bf16 v[10:13], v[226:229], v[214:217], v[10:13]
	v_mfma_f32_16x16x32_bf16 v[14:17], v[230:233], v[214:217], v[14:17]
	s_waitcnt vmcnt(5)
	v_mfma_f32_16x16x32_bf16 v[2:5], v[106:109], v[102:105], v[2:5]
	v_mfma_f32_16x16x32_bf16 v[6:9], v[110:113], v[102:105], v[6:9]
	v_mfma_f32_16x16x32_bf16 v[10:13], v[114:117], v[102:105], v[10:13]
	v_mfma_f32_16x16x32_bf16 v[14:17], v[118:121], v[102:105], v[14:17]
	s_waitcnt vmcnt(0)
	v_mfma_f32_16x16x32_bf16 v[2:5], v[160:163], v[156:159], v[2:5]
	v_mfma_f32_16x16x32_bf16 v[6:9], v[164:167], v[156:159], v[6:9]
	v_mfma_f32_16x16x32_bf16 v[10:13], v[168:171], v[156:159], v[10:13]
	v_mfma_f32_16x16x32_bf16 v[14:17], v[172:175], v[156:159], v[14:17]
	v_add_u32_e32 v22, v0, v79
	v_cmp_gt_i32_e32 vcc, s38, v22
	v_ashrrev_i32_e32 v23, 31, v22
	v_cndmask_b32_e32 v25, 0, v23, vcc
	s_nop 7
	ds_write_b128 v75, v[2:5]
	s_nop 3
	ds_write_b128 v75, v[6:9] offset:1024
	s_nop 0
	ds_write_b128 v75, v[10:13] offset:2048
	ds_write_b128 v75, v[14:17] offset:3072
	s_waitcnt lgkmcnt(0)
	s_barrier
	ds_read2st64_b32 v[6:7], v78 offset1:8
	ds_read2st64_b32 v[8:9], v78 offset0:16 offset1:24
	v_or_b32_e32 v2, s7, v77
	v_ashrrev_i32_e32 v3, 31, v2
	v_lshlrev_b64 v[4:5], 2, v[2:3]
	s_waitcnt lgkmcnt(1)
	v_add_f32_e32 v6, 0, v6
	s_waitcnt lgkmcnt(0)
	v_add_f32_e32 v6, v6, v8
	v_add_u32_e32 v8, 0xffffdf00, v22
	v_cndmask_b32_e32 v24, v8, v22, vcc
	v_lshlrev_b64 v[24:25], 13, v[24:25]
	v_lshl_add_u64 v[24:25], s[0:1], 0, v[24:25]
	v_lshl_add_u64 v[24:25], v[24:25], 0, v[4:5]
	global_load_dword v8, v[24:25], off
	ds_read2st64_b32 v[10:11], v78 offset0:32 offset1:40
	ds_read2st64_b32 v[12:13], v78 offset0:48 offset1:56
	ds_read2st64_b32 v[14:15], v78 offset0:64 offset1:72
	ds_read2st64_b32 v[16:17], v78 offset0:80 offset1:88
	ds_read2st64_b32 v[18:19], v78 offset0:96 offset1:104
	s_waitcnt lgkmcnt(4)
	v_add_f32_e32 v6, v6, v10
	ds_read2st64_b32 v[20:21], v78 offset0:112 offset1:120
	s_waitcnt lgkmcnt(4)
	v_add_f32_e32 v6, v6, v12
	s_waitcnt lgkmcnt(3)
	v_add_f32_e32 v6, v6, v14
	s_waitcnt lgkmcnt(2)
	v_add_f32_e32 v6, v6, v16
	s_waitcnt lgkmcnt(1)
	v_add_f32_e32 v6, v6, v18
	v_lshl_add_u64 v[2:3], s[10:11], 0, v[4:5]
	s_waitcnt lgkmcnt(0)
	v_add_f32_e32 v6, v6, v20
	v_lshlrev_b64 v[22:23], 13, v[22:23]
	v_lshl_add_u64 v[22:23], v[2:3], 0, v[22:23]
	s_waitcnt vmcnt(0)
	v_add_f32_e32 v6, v6, v8
	global_store_dword v[22:23], v6, off
	v_add_f32_e32 v6, 0, v7
	v_add_f32_e32 v6, v6, v9
	v_add_f32_e32 v6, v6, v11
	v_add_f32_e32 v6, v6, v13
	v_add_f32_e32 v6, v6, v15
	v_add_f32_e32 v6, v6, v17
	v_add_f32_e32 v6, v6, v19
	v_add_f32_e32 v10, v6, v21
	v_add_u32_e32 v6, v0, v80
	v_cmp_gt_i32_e32 vcc, s38, v6
	v_add_u32_e32 v0, 0xffffdf00, v6
	v_ashrrev_i32_e32 v7, 31, v6
	v_cndmask_b32_e32 v9, 0, v7, vcc
	v_cndmask_b32_e32 v8, v0, v6, vcc
	v_lshlrev_b64 v[8:9], 13, v[8:9]
	v_lshl_add_u64 v[8:9], s[0:1], 0, v[8:9]
	v_lshl_add_u64 v[4:5], v[8:9], 0, v[4:5]
	global_load_dword v0, v[4:5], off
	v_lshlrev_b64 v[4:5], 13, v[6:7]
	v_lshl_add_u64 v[2:3], v[2:3], 0, v[4:5]
	s_waitcnt vmcnt(0)
	v_add_f32_e32 v0, v10, v0
	global_store_dword v[2:3], v0, off
	s_barrier
	s_cbranch_scc1 .LBB0_1684
